# k16a: k15 + attention tile loop runs waves 4-7 at s_setprio 1 (static priority for the younger half)
# speedup vs baseline: 1.0399x; 1.0034x over previous
; #define LAS __attribute__((address_space(3)))
; __device__ __forceinline__ float lane0(float v) { return __builtin_bit_cast(float, __builtin_amdgcn_readfirstlane(__builtin_bit_cast(int, v))); }
; __device__ __forceinline__ void attn_unit(const UnitDesc& u, LAS unsigned char* shm, float qkmax, float thresh) {
;     ...
;     float carry = 0.f, Rown = 0.f, Rq0 = 0.f, inc4[4];
; #pragma unroll
;     for (int i = 0; i < 4; ++i) inc4[i] = suffix_incl(lfb[i], lane);
; #pragma unroll
;     for (int i = 0; i < 4; ++i) { if (i < nband) { const int jb = nband - 1 - i; const float R = carry + inc4[i] - lfb[i];
;         const float ro = __shfl(R, 32 * (wid & 1) + r32); if (jb == (wid >> 1)) Rown = ro;
;         if (jb == 0) Rq0 = __shfl(R, 0);
;         carry += lane0(inc4[i]); } }
;     const float ci = -Rown * LOG2E - qkmax;
;     const float kbq0 = Rq0 * LOG2E;
;     const int qabs = u.q0 + wid * 32 + r32;
;     float l_reg = 0.f; f32x16 o[2]; o[0] = f32x16{}; o[1] = f32x16{};
;     float lA = lfb[1], lB = lfb[2], lC = lfb[3];
;     { const float lf = lfb[0]; const float inc = inc4[0]; wsf[lane] = (inc - lf) * LOG2E; carry = lane0(inc);
;       *(LAS u32x4*)kdst = kreg; *(LAS u32x4*)vdst = vreg;
;       asm volatile("" : "+v"(qr[0]), "+v"(qr[1]), "+v"(qr[2]), "+v"(qr[3]));
;       asm volatile("s_waitcnt vmcnt(0)" : "+v"(kA), "+v"(vA), "+v"(kB), "+v"(vB), "+v"(kC), "+v"(vC) :: "memory"); }
;     int slot = 0, tile = NT - 1; bool stop = false;
.LBB0_772:
	v_lshlrev_b32_e32 v15, 1, v12
	s_lshl_b32 s12, s52, 10
	v_and_b32_e32 v15, 32, v15
	s_add_i32 s13, 0, 0x2000
	v_lshlrev_b32_e32 v142, 2, v136
	v_lshrrev_b32_e32 v12, 2, v12
	s_add_i32 s12, s12, 0
	v_add_u32_e32 v15, s13, v15
	v_and_or_b32 v12, v12, 3, v142
	s_lshl_b32 s13, s52, 9
	v_lshlrev_b32_e32 v12, 6, v12
	s_sub_i32 s53, s12, s13
	v_add_u32_e32 v147, s66, v10
	v_sub_f32_e32 v10, v0, v14
	v_lshl_add_u32 v143, v137, 4, s12
	v_add3_u32 v144, v15, v13, v12
	s_mov_b32 s12, 0xbfb8aa3b
	s_waitcnt lgkmcnt(0)
	v_mul_f32_e32 v146, 0x3fb8aa3b, v11
	v_mul_f32_e32 v10, 0x3fb8aa3b, v10
	v_lshl_add_u32 v11, v137, 2, s53
	v_mov_b32_e32 v14, v1
	v_mov_b32_e32 v15, v1
	v_lshlrev_b32_e32 v16, 10, v136
	v_lshlrev_b32_e32 v17, 4, v135
	v_fma_f32 v112, v21, s12, -v130
	v_mul_f32_e32 v197, 0x3fb8aa3b, v21
	s_mov_b64 s[98:99], 0
	s_nop 0
	v_readfirstlane_b32 s100, v197
	s_nop 3
	v_mov_b32_e32 v197, s100
	v_readfirstlane_b32 s100, v208
	s_nop 1
	s_lshr_b32 s100, s100, 8
	s_cmp_eq_u32 s100, 0
	s_cbranch_scc1 .Lmy_prio_skip
	s_setprio 1
.Lmy_prio_skip:
	ds_write_b32 v11, v10 offset:32768
	v_readfirstlane_b32 s12, v0
	ds_write_b128 v143, v[2:5]
	ds_write_b128 v143, v[6:9] offset:8192
	s_waitcnt vmcnt(0)
	v_mov_b32_e32 v0, v1
	v_mov_b32_e32 v2, v1
	v_mov_b32_e32 v3, v1
	v_mov_b32_e32 v4, v1
	v_mov_b32_e32 v5, v1
	v_mov_b32_e32 v6, v1
	v_mov_b32_e32 v7, v1
	v_mov_b32_e32 v8, v1
	v_mov_b32_e32 v9, v1
	v_mov_b32_e32 v10, v1
	v_mov_b32_e32 v11, v1
	v_mov_b32_e32 v12, v1
	v_mov_b32_e32 v13, v1
	v_mov_b64_e32 v[48:49], v[14:15]
	v_mov_b64_e32 v[64:65], v[14:15]
	v_mov_b64_e32 v[32:33], v[14:15]
	v_add3_u32 v145, 0, v16, v17
	s_add_i32 s73, s66, s49
	v_mov_b64_e32 v[46:47], v[12:13]
	v_mov_b64_e32 v[44:45], v[10:11]
	v_mov_b64_e32 v[42:43], v[8:9]
	v_mov_b64_e32 v[40:41], v[6:7]
	v_mov_b64_e32 v[38:39], v[4:5]
	v_mov_b64_e32 v[36:37], v[2:3]
	v_mov_b64_e32 v[34:35], v[0:1]
	v_mov_b64_e32 v[62:63], v[12:13]
	v_mov_b64_e32 v[60:61], v[10:11]
	v_mov_b64_e32 v[58:59], v[8:9]
	v_mov_b64_e32 v[56:57], v[6:7]
	v_mov_b64_e32 v[54:55], v[4:5]
	v_mov_b64_e32 v[52:53], v[2:3]
	v_mov_b64_e32 v[50:51], v[0:1]
	v_mov_b64_e32 v[30:31], v[12:13]
	v_mov_b64_e32 v[28:29], v[10:11]
	v_mov_b64_e32 v[26:27], v[8:9]
	v_mov_b64_e32 v[24:25], v[6:7]
	v_mov_b64_e32 v[22:23], v[4:5]
	v_mov_b64_e32 v[20:21], v[2:3]
	v_mov_b64_e32 v[18:19], v[0:1]
	v_mov_b64_e32 v[16:17], v[14:15]
	s_sub_i32 s72, s67, s28
	s_add_i32 s73, s73, 31
	v_mov_b32_e32 v113, v112
	v_mov_b32_e32 v114, v112
	v_mov_b32_e32 v115, v112
	v_mov_b32_e32 v116, v112
	v_mov_b32_e32 v117, v112
	v_mov_b32_e32 v118, v112
	v_mov_b32_e32 v119, v112
	v_mov_b32_e32 v120, v112
	v_mov_b32_e32 v121, v112
	v_mov_b32_e32 v122, v112
	v_mov_b32_e32 v123, v112
	v_mov_b32_e32 v124, v112
	v_mov_b32_e32 v125, v112
	v_mov_b32_e32 v126, v112
	v_mov_b32_e32 v127, v112
	s_lshl_b32 s75, s67, 6
	s_mov_b32 s70, 0
	v_mov_b32_e32 v148, 0
	s_mov_b64 s[62:63], 0
	v_mov_b32_e32 v150, s12
	v_mov_b64_e32 v[14:15], v[12:13]
	v_mov_b64_e32 v[12:13], v[10:11]
	v_mov_b64_e32 v[10:11], v[8:9]
	v_mov_b64_e32 v[8:9], v[6:7]
	v_mov_b64_e32 v[6:7], v[4:5]
	v_mov_b64_e32 v[4:5], v[2:3]
	v_mov_b64_e32 v[2:3], v[0:1]
	s_branch .LBB0_777

; #define LAS __attribute__((address_space(3)))
; __device__ __forceinline__ void attn_unit(const UnitDesc& u, LAS unsigned char* shm, float qkmax, float thresh) {
;     ...
;     asm volatile("s_waitcnt vmcnt(0)" : "+v"(kA), "+v"(vA), "+v"(kB), "+v"(vB), "+v"(kC), "+v"(vC), "+v"(lA), "+v"(lB), "+v"(lC) :: "memory");
;     if (active) {
;         u32x4 zv4[4];
; #pragma unroll
;         for (int i = 0; i < 4; ++i) zv4[i] = *(const u32x4*)(u.Zg + (size_t)(wid * 32 + i * 8 + (lane >> 3)) * 512 + (lane & 7) * 8);
;         { auto rr = __builtin_amdgcn_permlane32_swap(__float_as_uint(l_reg), __float_as_uint(l_reg), false, false); l_reg = __uint_as_float(rr[0]) + __uint_as_float(rr[1]); }
;         LAS float* lx = (LAS float*)(shm + LDS_LX) + wid * 32;
;         if (hi == 0) lx[r32] = l_reg;
.LBB0_829:
	s_or_b64 exec, exec, s[62:63]
	s_setprio 0
	s_waitcnt vmcnt(0)
	s_and_b64 vcc, exec, s[12:13]
	s_cbranch_vccnz .LBB0_719
	s_nop 7
	s_nop 7
	v_mov_b64_e32 v[34:35], v[2:3]
	v_mov_b64_e32 v[36:37], v[4:5]
	v_mov_b64_e32 v[38:39], v[6:7]
	v_mov_b64_e32 v[40:41], v[8:9]
	v_mov_b64_e32 v[42:43], v[10:11]
	v_mov_b64_e32 v[44:45], v[12:13]
	v_mov_b64_e32 v[46:47], v[14:15]
	v_mov_b64_e32 v[48:49], v[16:17]
	v_mov_b64_e32 v[50:51], v[18:19]
	v_mov_b64_e32 v[52:53], v[20:21]
	v_mov_b64_e32 v[54:55], v[22:23]
	v_mov_b64_e32 v[56:57], v[24:25]
	v_mov_b64_e32 v[58:59], v[26:27]
	v_mov_b64_e32 v[60:61], v[28:29]
	v_mov_b64_e32 v[62:63], v[30:31]
	v_mov_b64_e32 v[64:65], v[32:33]
	s_lshl_b64 s[6:7], s[44:45], 1
	s_add_u32 s8, s24, s6
	v_lshrrev_b32_e32 v20, 3, v137
	s_addc_u32 s9, s25, s7
	s_lshl_b64 s[6:7], s[46:47], 1
	v_or_b32_e32 v18, s49, v20
	s_add_u32 s8, s8, s6
	v_and_b32_e32 v0, 56, v138
	v_or_b32_e32 v6, 8, v18
	s_addc_u32 s9, s9, s7
	v_lshlrev_b32_e32 v0, 1, v0
	v_ashrrev_i32_e32 v19, 31, v18
	v_ashrrev_i32_e32 v7, 31, v6
	v_lshl_add_u64 v[2:3], s[8:9], 0, v[0:1]
	v_lshlrev_b64 v[4:5], 10, v[18:19]
	v_lshlrev_b64 v[6:7], 10, v[6:7]
	v_lshl_add_u64 v[4:5], v[2:3], 0, v[4:5]
	v_lshl_add_u64 v[6:7], v[2:3], 0, v[6:7]
	global_load_dwordx4 v[14:17], v[4:5], off
	global_load_dwordx4 v[10:13], v[6:7], off
	v_or_b32_e32 v4, 16, v18
	v_or_b32_e32 v6, 24, v18
	v_ashrrev_i32_e32 v5, 31, v4
	v_ashrrev_i32_e32 v7, 31, v6
	v_lshlrev_b64 v[4:5], 10, v[4:5]
	v_lshlrev_b64 v[6:7], 10, v[6:7]
	v_lshl_add_u64 v[4:5], v[2:3], 0, v[4:5]
	v_lshl_add_u64 v[2:3], v[2:3], 0, v[6:7]
	global_load_dwordx4 v[6:9], v[4:5], off
	s_nop 0
	global_load_dwordx4 v[2:5], v[2:3], off
	v_mov_b32_e32 v21, v148
	s_lshl_b32 s8, s49, 2
	s_nop 0
	v_permlane32_swap_b32_e32 v148, v21
	s_add_i32 s10, s8, 0
	v_cmp_gt_u32_e32 vcc, 32, v137
	s_and_saveexec_b64 s[8:9], vcc
	s_cbranch_execz .LBB0_718
	v_add_f32_e32 v21, v148, v21
	v_lshl_add_u32 v22, v135, 2, s10
	ds_write_b32 v22, v21 offset:36864
	s_branch .LBB0_718
